# P3: GLA-A units rebalanced between the grid halves (first half has one more 256x256 GEMM unit in this phase)
# speedup vs baseline: 1.0156x; 1.0156x over previous
.LBB0_624:
	s_add_i32 s38, s26, s33
	s_cmp_lg_u32 s33, 0x100
	s_cbranch_scc1 .Lga_norule
	s_sub_i32 s4, s38, 0x800
	s_cmp_lt_u32 s4, 0x80
	s_cselect_b32 s38, 0xa00, s38
	s_sub_i32 s4, s26, 0x980
	s_sub_i32 s5, s26, 0x180
	s_cmp_lt_u32 s4, 0x80
	s_cselect_b32 s38, s5, s38
.Lga_norule:
	s_lshl_b32 s2, s38, 6
	s_lshl_b32 s35, s38, 1
	s_add_i32 s35, s35, 0x7ffff000
	s_cmpk_gt_i32 s38, 0x9ff
	s_cselect_b64 s[4:5], -1, 0
	s_and_b64 vcc, exec, s[4:5]
	s_cbranch_vccnz .LBB0_650
	s_cmpk_gt_i32 s38, 0x7ff
	s_mov_b64 s[28:29], -1
	s_cbranch_scc0 .LBB0_627
	s_and_b32 s10, s35, 0x7ffffff8
	s_add_i32 s10, s10, 0x8000
	s_and_b32 s27, s38, 3
	s_mov_b64 s[28:29], 0
